# DA wave roles remapped (query group = wid&3, softmax map = wid>>2) so the serial unit epilogue of the map-0 waves spreads over all four SIMDs; NA stages key rows {s, s+8} per step
# speedup vs baseline: 1.0588x; 1.0125x over previous
; __device__ __forceinline__ float bflo(unsigned w) { return __uint_as_float(w << 16); }
; __device__ __forceinline__ float bfhi(unsigned w) { return __uint_as_float(w & 0xffff0000u); }
; __device__ void na_super(char* lds, const Params& p, int layer, int su) {
;     int tid_ = threadIdx.x; asm volatile("" : "+v"(tid_)); const int tid = tid_, lane = tid & 63, wid = __builtin_amdgcn_readfirstlane(tid >> 6), fr = lane & 15, fq = lane >> 4;
;     const int bh = (su & 7) * 8 + (su >> 5), g = (su >> 3) & 3, b = bh >> 3, h = bh & 7;
;     const float* rph = (const float*)(lds + LDS_RPB_OFF) + h * 465;
;     const float c1 = 0.125f * LOG2E;
;     const int rq = 8 * g + wid, rsw = min(max(rq - 4, 0), 24);
;     bf16x8 qf[4][2];
;     f32x4 O[4][4];
;     float mrow[4], lrow[4];
; #pragma unroll
;     for (int n = 0; n < 4; ++n) {
; #pragma unroll
;         for (int t = 0; t < 2; ++t) qf[n][t] = *(const bf16x8*)(p.z + ZS_QN + ((size_t)(bh * 2048 + rq * 64 + 16 * n + fr)) * 64 + t * 32 + fq * 8);
; #pragma unroll
;         for (int dt = 0; dt < 4; ++dt) O[n][dt] = (f32x4){0.f, 0.f, 0.f, 0.f};
;         lrow[n] = 0.f;
;         {
;             const u32x4 k0 = *(const u32x4*)(p.z + ZS_KN + ((size_t)(bh * 2048 + rq * 64 + 16 * n + fr)) * 64 + fq * 8);
;             const u32x4 k1 = *(const u32x4*)(p.z + ZS_KN + ((size_t)(bh * 2048 + rq * 64 + 16 * n + fr)) * 64 + 32 + fq * 8);
;             const u32x4 q0 = __builtin_bit_cast(u32x4, qf[n][0]), q1 = __builtin_bit_cast(u32x4, qf[n][1]);
;             float d = 0.f;
; #pragma unroll
;             for (int w = 0; w < 4; ++w) { d += bflo(q0[w]) * bflo(k0[w]) + bfhi(q0[w]) * bfhi(k0[w]); d += bflo(q1[w]) * bflo(k1[w]) + bfhi(q1[w]) * bfhi(k1[w]); }
;             d += __shfl_xor(d, 16); d += __shfl_xor(d, 32);
;             mrow[n] = -d;
;         }
;     }
.LBB0_452:
	s_cmpk_gt_i32 s21, 0x1ff
	s_mov_b64 s[0:1], -1
	s_cbranch_scc0 .LBB0_475
	v_mov_b32_e32 v139, v245
	s_add_i32 s0, s21, 0xfffffe00
	s_lshr_b32 s33, s0, 5
	v_readfirstlane_b32 s1, v139
	s_ashr_i32 s74, s1, 6
	s_lshl_b32 s1, s0, 3
	s_and_b32 s73, s1, 56
	s_bfe_u32 s1, s21, 0x20003
	s_lshl_b32 s3, s1, 3
	s_or_b32 s0, s73, s33
	s_add_i32 s74, s74, s3
	s_lshl_b32 s2, s0, 11
	s_lshl_b32 s75, s74, 6
	s_waitcnt vmcnt(12)
	v_and_b32_e32 v141, 15, v139
	s_add_i32 s2, s75, s2
	v_or_b32_e32 v8, s2, v141
	v_and_b32_e32 v128, 48, v139
	v_mov_b32_e32 v129, v153
	v_ashrrev_i32_e32 v9, 31, v8
	v_readlane_b32 s8, v254, 16
	v_lshl_add_u64 v[10:11], s[76:77], 0, v[128:129]
	v_lshlrev_b64 v[0:1], 7, v[8:9]
	v_readlane_b32 s9, v254, 17
	v_lshl_add_u64 v[2:3], v[10:11], 0, v[0:1]
	global_load_dwordx4 v[56:59], v[2:3], off
	global_load_dwordx4 v[60:63], v[2:3], off offset:64
	v_lshl_add_u64 v[0:1], s[8:9], 0, v[0:1]
	v_lshl_add_u64 v[0:1], v[0:1], 0, v[128:129]
	global_load_dwordx4 v[12:15], v[0:1], off
	global_load_dwordx4 v[16:19], v[0:1], off offset:64
	v_and_b32_e32 v0, 64, v240
	v_add_u32_e32 v9, 64, v0
	v_or_b32_e32 v0, 16, v8
	v_ashrrev_i32_e32 v1, 31, v0
	v_lshlrev_b64 v[0:1], 7, v[0:1]
	v_lshl_add_u64 v[2:3], v[10:11], 0, v[0:1]
	v_lshl_add_u64 v[0:1], s[8:9], 0, v[0:1]
	v_lshl_add_u64 v[0:1], v[0:1], 0, v[128:129]
	global_load_dwordx4 v[64:67], v[2:3], off
	global_load_dwordx4 v[68:71], v[2:3], off offset:64
	global_load_dwordx4 v[20:23], v[0:1], off
	global_load_dwordx4 v[24:27], v[0:1], off offset:64
	v_xor_b32_e32 v4, 16, v240
	v_cmp_lt_i32_e32 vcc, v4, v9
	s_mul_i32 s4, s33, 0x744
	s_max_i32 s5, s74, 4
	v_cndmask_b32_e32 v0, v240, v4, vcc
	v_lshlrev_b32_e32 v142, 2, v0
	v_or_b32_e32 v0, 32, v8
	v_ashrrev_i32_e32 v1, 31, v0
	v_lshlrev_b64 v[0:1], 7, v[0:1]
	v_lshl_add_u64 v[2:3], v[10:11], 0, v[0:1]
	v_lshl_add_u64 v[0:1], s[8:9], 0, v[0:1]
	v_lshl_add_u64 v[4:5], v[0:1], 0, v[128:129]
	global_load_dwordx4 v[76:79], v[2:3], off
	global_load_dwordx4 v[80:83], v[2:3], off offset:64
	s_nop 0
	global_load_dwordx4 v[0:3], v[4:5], off
	s_nop 0
	global_load_dwordx4 v[4:7], v[4:5], off offset:64
	v_or_b32_e32 v8, 48, v8
	s_add_i32 s5, s5, -4
	s_add_i32 s70, s4, 0
	s_add_i32 s70, s70, 0x23090
	s_min_u32 s92, s5, 24
	s_cmp_eq_u32 s1, 0
	s_cselect_b64 s[4:5], -1, 0
	s_cmp_eq_u32 s1, 3
	s_cselect_b64 s[6:7], -1, 0
	s_or_b64 s[4:5], s[4:5], s[6:7]
	s_and_b64 s[4:5], s[4:5], exec
	s_cselect_b32 s96, 6, 8
	s_lshl_b32 s0, s0, 18
	v_bfe_u32 v138, v139, 4, 2
	v_lshlrev_b32_e32 v152, 3, v138
	s_mov_b32 s85, s21
	v_mov_b32_e32 v134, v153
	v_mov_b32_e32 v135, v153
	v_and_b32_e32 v140, 63, v139
	s_mov_b32 s2, 0
	v_mul_u32_u24_e32 v145, 0x90, v141
	v_mov_b64_e32 v[136:137], v[134:135]
	s_waitcnt vmcnt(11)
	v_and_b32_e32 v31, 0xffff0000, v56
	s_waitcnt vmcnt(10)
	v_and_b32_e32 v30, 0xffff0000, v60
	v_lshlrev_b32_e32 v29, 16, v56
	s_waitcnt vmcnt(9)
	v_and_b32_e32 v47, 0xffff0000, v12
	s_waitcnt vmcnt(8)
	v_and_b32_e32 v46, 0xffff0000, v16
	v_lshlrev_b32_e32 v28, 16, v60
	v_lshlrev_b32_e32 v45, 16, v12
	v_lshlrev_b32_e32 v44, 16, v16
	v_pk_mul_f32 v[30:31], v[30:31], v[46:47]
	v_and_b32_e32 v35, 0xffff0000, v57
	v_and_b32_e32 v34, 0xffff0000, v61
	v_lshlrev_b32_e32 v49, 16, v13
	v_and_b32_e32 v13, 0xffff0000, v13
	v_and_b32_e32 v12, 0xffff0000, v17
	v_pk_fma_f32 v[28:29], v[28:29], v[44:45], v[30:31]
	v_lshlrev_b32_e32 v33, 16, v57
	v_lshlrev_b32_e32 v32, 16, v61
	v_lshlrev_b32_e32 v48, 16, v17
	v_lshlrev_b32_e32 v17, 16, v14
	v_and_b32_e32 v51, 0xffff0000, v14
	v_pk_mul_f32 v[12:13], v[34:35], v[12:13]
	v_add_f32_e32 v14, 0, v29
	v_and_b32_e32 v39, 0xffff0000, v58
	v_and_b32_e32 v38, 0xffff0000, v62
	v_and_b32_e32 v50, 0xffff0000, v18
	v_pk_fma_f32 v[12:13], v[32:33], v[48:49], v[12:13]
	v_add_f32_e32 v14, v28, v14
	v_lshlrev_b32_e32 v37, 16, v58
	v_lshlrev_b32_e32 v36, 16, v62
	v_lshlrev_b32_e32 v16, 16, v18
	v_pk_mul_f32 v[34:35], v[38:39], v[50:51]
	v_add_f32_e32 v13, v13, v14
	v_pk_fma_f32 v[16:17], v[36:37], v[16:17], v[34:35]
	v_add_f32_e32 v12, v12, v13
	v_and_b32_e32 v43, 0xffff0000, v59
	v_and_b32_e32 v42, 0xffff0000, v63
	v_lshlrev_b32_e32 v53, 16, v15
	v_and_b32_e32 v15, 0xffff0000, v15
	v_add_f32_e32 v12, v17, v12
	v_and_b32_e32 v14, 0xffff0000, v19
	v_lshlrev_b32_e32 v41, 16, v59
	v_lshlrev_b32_e32 v40, 16, v63
	v_lshlrev_b32_e32 v52, 16, v19
	v_add_f32_e32 v16, v16, v12
	v_pk_mul_f32 v[12:13], v[42:43], v[14:15]
	v_xor_b32_e32 v14, 32, v240
	v_pk_fma_f32 v[12:13], v[40:41], v[52:53], v[12:13]
	v_cmp_lt_i32_e32 vcc, v14, v9
	v_add_f32_e32 v13, v13, v16
	v_add_f32_e32 v12, v12, v13
	ds_bpermute_b32 v13, v142, v12
	v_cndmask_b32_e32 v9, v240, v14, vcc
	v_lshlrev_b32_e32 v143, 2, v9
	s_waitcnt vmcnt(7)
	v_and_b32_e32 v17, 0xffff0000, v64
	s_waitcnt vmcnt(6)
	v_and_b32_e32 v16, 0xffff0000, v68
	s_waitcnt lgkmcnt(0)
	v_add_f32_e32 v9, v12, v13
	ds_bpermute_b32 v12, v143, v9
	s_waitcnt vmcnt(5)
	v_and_b32_e32 v19, 0xffff0000, v20
	s_waitcnt vmcnt(4)
	v_and_b32_e32 v18, 0xffff0000, v24
	v_lshlrev_b32_e32 v13, 16, v64
	v_lshlrev_b32_e32 v15, 16, v20
	s_waitcnt lgkmcnt(0)
; __device__ __forceinline__ float bflo(unsigned w) { return __uint_as_float(w << 16); }
; __device__ __forceinline__ float bfhi(unsigned w) { return __uint_as_float(w & 0xffff0000u); }
; __device__ void na_super(char* lds, const Params& p, int layer, int su) {
;     ...
;             const u32x4 k0 = *(const u32x4*)(p.z + ZS_KN + ((size_t)(bh * 2048 + rq * 64 + 16 * n + fr)) * 64 + fq * 8);
;             const u32x4 k1 = *(const u32x4*)(p.z + ZS_KN + ((size_t)(bh * 2048 + rq * 64 + 16 * n + fr)) * 64 + 32 + fq * 8);
;             const u32x4 q0 = __builtin_bit_cast(u32x4, qf[n][0]), q1 = __builtin_bit_cast(u32x4, qf[n][1]);
;             float d = 0.f;
; #pragma unroll
;             for (int w = 0; w < 4; ++w) { d += bflo(q0[w]) * bflo(k0[w]) + bfhi(q0[w]) * bfhi(k0[w]); d += bflo(q1[w]) * bflo(k1[w]) + bfhi(q1[w]) * bfhi(k1[w]); }
;             d += __shfl_xor(d, 16); d += __shfl_xor(d, 32);
;             mrow[n] = -d;
;         }
;     }
;     const int klo = min(max(8 * g - 4, 0), 24);
;     const int nsteps = (g == 0 || g == 3) ? 6 : 8;
;     const bf16_t* Kg = p.z + ZS_KN + ((size_t)(bh * 2048 + klo * 64)) * 64 + tid * 8;
;     const bf16_t* Vg = p.vT + VS_VN + ((size_t)((bh * 32 + klo) * 64)) * 64 + tid * 8;
;     const int lw = (tid >> 3) * NA_P + (tid & 7) * 16;
;     u32x4 rk[2], rv[2];
;     rk[0] = *(const u32x4*)(Kg); rk[1] = *(const u32x4*)(Kg + 4096);
;     rv[0] = *(const u32x4*)(Vg); rv[1] = *(const u32x4*)(Vg + 4096);
;     __syncthreads();
;     *(u32x4*)(lds + lw) = rk[0]; *(u32x4*)(lds + lw + 64 * NA_P) = rk[1];
;     *(u32x4*)(lds + NA_KBYTES + lw) = rv[0]; *(u32x4*)(lds + NA_KBYTES + lw + 64 * NA_P) = rv[1];
;     __syncthreads();
	v_add_f32_e32 v9, v9, v12
	v_lshlrev_b32_e32 v12, 16, v68
	v_lshlrev_b32_e32 v14, 16, v24
	v_pk_mul_f32 v[16:17], v[16:17], v[18:19]
	v_xor_b32_e32 v84, 0x80000000, v9
	v_pk_fma_f32 v[12:13], v[12:13], v[14:15], v[16:17]
	v_and_b32_e32 v17, 0xffff0000, v65
	v_add_f32_e32 v9, 0, v13
	v_and_b32_e32 v16, 0xffff0000, v69
	v_and_b32_e32 v19, 0xffff0000, v21
	v_and_b32_e32 v18, 0xffff0000, v25
	v_add_f32_e32 v9, v12, v9
	v_lshlrev_b32_e32 v13, 16, v65
	v_lshlrev_b32_e32 v12, 16, v69
	v_lshlrev_b32_e32 v15, 16, v21
	v_lshlrev_b32_e32 v14, 16, v25
	v_pk_mul_f32 v[16:17], v[16:17], v[18:19]
	v_and_b32_e32 v19, 0xffff0000, v22
	v_pk_fma_f32 v[12:13], v[12:13], v[14:15], v[16:17]
	v_and_b32_e32 v17, 0xffff0000, v66
	v_add_f32_e32 v9, v13, v9
	v_and_b32_e32 v16, 0xffff0000, v70
	v_and_b32_e32 v18, 0xffff0000, v26
	v_add_f32_e32 v9, v12, v9
	v_lshlrev_b32_e32 v13, 16, v66
	v_lshlrev_b32_e32 v12, 16, v70
	v_lshlrev_b32_e32 v15, 16, v22
	v_lshlrev_b32_e32 v14, 16, v26
	v_pk_mul_f32 v[16:17], v[16:17], v[18:19]
	v_and_b32_e32 v19, 0xffff0000, v23
	v_pk_fma_f32 v[12:13], v[12:13], v[14:15], v[16:17]
	v_and_b32_e32 v17, 0xffff0000, v67
	v_add_f32_e32 v9, v13, v9
	v_and_b32_e32 v16, 0xffff0000, v71
	v_and_b32_e32 v18, 0xffff0000, v27
	v_add_f32_e32 v9, v12, v9
	v_lshlrev_b32_e32 v13, 16, v67
	v_lshlrev_b32_e32 v12, 16, v71
	v_lshlrev_b32_e32 v15, 16, v23
	v_lshlrev_b32_e32 v14, 16, v27
	v_pk_mul_f32 v[16:17], v[16:17], v[18:19]
	s_waitcnt vmcnt(1)
	v_lshlrev_b32_e32 v19, 16, v0
	v_pk_fma_f32 v[12:13], v[12:13], v[14:15], v[16:17]
	v_and_b32_e32 v15, 0xffff0000, v0
	v_add_f32_e32 v9, v13, v9
	v_add_f32_e32 v22, v12, v9
	v_ashrrev_i32_e32 v9, 31, v8
	v_lshlrev_b64 v[8:9], 7, v[8:9]
	v_and_b32_e32 v13, 0xffff0000, v76
	v_and_b32_e32 v12, 0xffff0000, v80
	s_waitcnt vmcnt(0)
	v_and_b32_e32 v14, 0xffff0000, v4
	v_lshl_add_u64 v[10:11], v[10:11], 0, v[8:9]
	v_lshl_add_u64 v[8:9], s[8:9], 0, v[8:9]
	v_pk_mul_f32 v[20:21], v[12:13], v[14:15]
	v_lshl_add_u64 v[12:13], v[8:9], 0, v[128:129]
	global_load_dwordx4 v[92:95], v[10:11], off
	global_load_dwordx4 v[96:99], v[10:11], off offset:64
	s_nop 0
	global_load_dwordx4 v[8:11], v[12:13], off
	s_nop 0
	global_load_dwordx4 v[12:15], v[12:13], off offset:64
	v_lshlrev_b32_e32 v17, 16, v76
	v_lshlrev_b32_e32 v16, 16, v80
	v_lshlrev_b32_e32 v18, 16, v4
	v_pk_fma_f32 v[16:17], v[16:17], v[18:19], v[20:21]
	v_lshlrev_b32_e32 v19, 16, v1
	v_add_f32_e32 v0, 0, v17
	v_add_f32_e32 v4, v16, v0
	v_and_b32_e32 v21, 0xffff0000, v77
	v_and_b32_e32 v20, 0xffff0000, v81
	v_and_b32_e32 v1, 0xffff0000, v1
	v_and_b32_e32 v0, 0xffff0000, v5
	v_lshlrev_b32_e32 v17, 16, v77
	v_lshlrev_b32_e32 v16, 16, v81
	v_lshlrev_b32_e32 v18, 16, v5
	v_pk_mul_f32 v[0:1], v[20:21], v[0:1]
	v_lshlrev_b32_e32 v5, 16, v2
	v_pk_fma_f32 v[0:1], v[16:17], v[18:19], v[0:1]
	v_and_b32_e32 v19, 0xffff0000, v2
	v_sub_u32_e64 v2, s3, 4 clamp
	v_and_b32_e32 v17, 0xffff0000, v78
	v_readfirstlane_b32 s93, v2
	v_and_b32_e32 v16, 0xffff0000, v82
	v_and_b32_e32 v18, 0xffff0000, v6
	s_lshl_b32 s1, s93, 13
	v_pk_mul_f32 v[16:17], v[16:17], v[18:19]
	s_or_b32 s3, s1, s0
	v_lshlrev_b32_e32 v18, 3, v139
	s_add_u32 s0, s8, s3
	v_ashrrev_i32_e32 v19, 31, v18
	s_addc_u32 s1, s9, 0
	v_lshlrev_b64 v[18:19], 1, v[18:19]
	v_lshl_add_u64 v[130:131], s[0:1], 0, v[18:19]
	s_add_u32 s0, s68, s3
	s_addc_u32 s1, s69, 0
	v_lshl_add_u64 v[132:133], s[0:1], 0, v[18:19]
	v_add_co_u32_e32 v18, vcc, 0x10000, v130
	global_load_dwordx4 v[100:103], v[130:131], off
	s_nop 0
	v_addc_co_u32_e32 v19, vcc, 0, v131, vcc
	global_load_dwordx4 v[104:107], v[18:19], off
	global_load_dwordx4 v[108:111], v[132:133], off
	v_add_co_u32_e32 v18, vcc, 0x10000, v132
	v_add_f32_e32 v1, v1, v4
	s_nop 0
	v_addc_co_u32_e32 v19, vcc, 0, v133, vcc
	global_load_dwordx4 v[112:115], v[18:19], off
	v_add_f32_e32 v20, v0, v1
	v_lshlrev_b32_e32 v1, 16, v78
	v_lshlrev_b32_e32 v0, 16, v82
	v_lshlrev_b32_e32 v4, 16, v6
	v_pk_fma_f32 v[0:1], v[0:1], v[4:5], v[16:17]
	v_lshlrev_b32_e32 v5, 16, v3
	v_add_f32_e32 v1, v1, v20
	v_and_b32_e32 v17, 0xffff0000, v79
	v_and_b32_e32 v16, 0xffff0000, v83
	v_and_b32_e32 v3, 0xffff0000, v3
	v_and_b32_e32 v2, 0xffff0000, v7
	v_add_f32_e32 v6, v0, v1
	v_lshlrev_b32_e32 v1, 16, v79
	v_lshlrev_b32_e32 v0, 16, v83
	v_lshlrev_b32_e32 v4, 16, v7
	v_pk_mul_f32 v[2:3], v[16:17], v[2:3]
	ds_bpermute_b32 v23, v142, v22
	v_pk_fma_f32 v[0:1], v[0:1], v[4:5], v[2:3]
	s_movk_i32 s0, 0x90
	v_add_f32_e32 v1, v1, v6
	v_add_f32_e32 v16, v0, v1
	ds_bpermute_b32 v17, v142, v16
	v_mov_b32_e32 v48, v153
	v_mov_b32_e32 v49, v153
	v_mov_b32_e32 v50, v153
	v_mov_b32_e32 v51, v153
	v_mov_b64_e32 v[54:55], v[50:51]
	v_mov_b64_e32 v[74:75], v[50:51]
	v_mov_b64_e32 v[90:91], v[50:51]
	v_mov_b64_e32 v[44:45], v[48:49]
	s_waitcnt vmcnt(7)
	v_and_b32_e32 v5, 0xffff0000, v92
	s_waitcnt vmcnt(6)
	v_and_b32_e32 v4, 0xffff0000, v96
	s_waitcnt vmcnt(5)
	v_and_b32_e32 v7, 0xffff0000, v8
	s_waitcnt vmcnt(4)
; __device__ void na_super(char* lds, const Params& p, int layer, int su) {
;     ...
;             d += __shfl_xor(d, 16); d += __shfl_xor(d, 32);
;             mrow[n] = -d;
;         }
;     }
;     const int klo = min(max(8 * g - 4, 0), 24);
;     const int nsteps = (g == 0 || g == 3) ? 6 : 8;
;     const bf16_t* Kg = p.z + ZS_KN + ((size_t)(bh * 2048 + klo * 64)) * 64 + tid * 8;
;     const bf16_t* Vg = p.vT + VS_VN + ((size_t)((bh * 32 + klo) * 64)) * 64 + tid * 8;
;     const int lw = (tid >> 3) * NA_P + (tid & 7) * 16;
;     u32x4 rk[2], rv[2];
;     rk[0] = *(const u32x4*)(Kg); rk[1] = *(const u32x4*)(Kg + 4096);
;     rv[0] = *(const u32x4*)(Vg); rv[1] = *(const u32x4*)(Vg + 4096);
;     __syncthreads();
;     *(u32x4*)(lds + lw) = rk[0]; *(u32x4*)(lds + lw + 64 * NA_P) = rk[1];
;     *(u32x4*)(lds + NA_KBYTES + lw) = rv[0]; *(u32x4*)(lds + NA_KBYTES + lw + 64 * NA_P) = rv[1];
;     __syncthreads();
;     const int krow_off = (8 * (fr >> 2) + (fr & 3)) * NA_P + fq * 16;
;     const int vrow_off = fr * NA_P + (8 * fq) * 2;
;     for (int st = 0; st < nsteps; ++st) {
;         const char* cur = lds + (st & 1) * NA_STAGE;
;         char* nxt = lds + ((st + 1) & 1) * NA_STAGE;
;         if (st + 1 < nsteps) {
;             const bf16_t* kg = Kg + (size_t)(st + 1) * 8192; const bf16_t* vg = Vg + (size_t)(st + 1) * 8192;
;             rk[0] = *(const u32x4*)(kg); rk[1] = *(const u32x4*)(kg + 4096);
;             rv[0] = *(const u32x4*)(vg); rv[1] = *(const u32x4*)(vg + 4096);
;         }
; #pragma unroll 1
;         for (int slot = 0; slot < 2; ++slot) {
;             const int kr = klo + 2 * st + slot;
;             if (kr >= rsw && kr <= rsw + 7) {
;                 const char* cK = cur + slot * 64 * NA_P + krow_off;
;                 const char* cV = cur + NA_KBYTES + slot * 64 * NA_P + vrow_off;
;                 const float* rpr = rph + (kr - rq + 7) * 31;
;                 float v[4][8];
; #pragma unroll
;                 for (int n = 0; n < 4; ++n) {
;                     const int kcstart = n == 0 ? 0 : (n == 1 ? 8 : (n == 2 ? 24 : 32));
;                     const int qcol = 16 * n + fr;
;                     const float* bp = rpr + (kcstart + 8 * fq - qcol + 15);
; #pragma unroll
;                     for (int e = 0; e < 8; ++e) v[n][e] = bp[e];
;                 }
; #pragma unroll
;                 for (int np = 0; np < 2; ++np) {
	v_and_b32_e32 v6, 0xffff0000, v12
	v_lshlrev_b32_e32 v1, 16, v92
	v_lshlrev_b32_e32 v0, 16, v96
	v_lshlrev_b32_e32 v3, 16, v8
	v_lshlrev_b32_e32 v2, 16, v12
	v_pk_mul_f32 v[4:5], v[4:5], v[6:7]
	v_and_b32_e32 v7, 0xffff0000, v9
	v_pk_fma_f32 v[0:1], v[0:1], v[2:3], v[4:5]
	v_and_b32_e32 v5, 0xffff0000, v93
	v_add_f32_e32 v1, 0, v1
	v_and_b32_e32 v4, 0xffff0000, v97
	v_and_b32_e32 v6, 0xffff0000, v13
	v_add_f32_e32 v8, v0, v1
	v_lshlrev_b32_e32 v1, 16, v93
	v_lshlrev_b32_e32 v0, 16, v97
	v_lshlrev_b32_e32 v3, 16, v9
	v_lshlrev_b32_e32 v2, 16, v13
	v_pk_mul_f32 v[4:5], v[4:5], v[6:7]
	v_and_b32_e32 v7, 0xffff0000, v10
	v_pk_fma_f32 v[0:1], v[0:1], v[2:3], v[4:5]
	v_and_b32_e32 v5, 0xffff0000, v94
	v_add_f32_e32 v1, v1, v8
	v_and_b32_e32 v4, 0xffff0000, v98
	v_and_b32_e32 v6, 0xffff0000, v14
	v_add_f32_e32 v8, v0, v1
	v_lshlrev_b32_e32 v1, 16, v94
	v_lshlrev_b32_e32 v0, 16, v98
	v_lshlrev_b32_e32 v3, 16, v10
	v_lshlrev_b32_e32 v2, 16, v14
	v_pk_mul_f32 v[4:5], v[4:5], v[6:7]
	v_and_b32_e32 v7, 0xffff0000, v11
	v_pk_fma_f32 v[0:1], v[0:1], v[2:3], v[4:5]
	v_and_b32_e32 v5, 0xffff0000, v95
	v_add_f32_e32 v1, v1, v8
	v_and_b32_e32 v4, 0xffff0000, v99
	v_and_b32_e32 v6, 0xffff0000, v15
	v_add_f32_e32 v8, v0, v1
	v_lshlrev_b32_e32 v1, 16, v95
	v_lshlrev_b32_e32 v0, 16, v99
	v_lshlrev_b32_e32 v3, 16, v11
	v_lshlrev_b32_e32 v2, 16, v15
	v_pk_mul_f32 v[4:5], v[4:5], v[6:7]
	v_mov_b64_e32 v[40:41], v[48:49]
	v_pk_fma_f32 v[0:1], v[0:1], v[2:3], v[4:5]
	s_waitcnt lgkmcnt(1)
	v_add_f32_e32 v2, v22, v23
	v_add_f32_e32 v1, v1, v8
	v_add_f32_e32 v0, v0, v1
	ds_bpermute_b32 v1, v142, v0
	ds_bpermute_b32 v3, v143, v2
	s_waitcnt lgkmcnt(2)
	v_add_f32_e32 v4, v16, v17
	ds_bpermute_b32 v5, v143, v4
	v_mov_b64_e32 v[36:37], v[48:49]
	s_waitcnt lgkmcnt(2)
	v_add_f32_e32 v0, v0, v1
	ds_bpermute_b32 v1, v143, v0
	s_waitcnt lgkmcnt(2)
	v_add_f32_e32 v2, v2, v3
	v_xor_b32_e32 v116, 0x80000000, v2
	s_waitcnt lgkmcnt(1)
	v_add_f32_e32 v2, v4, v5
	v_xor_b32_e32 v120, 0x80000000, v2
	s_waitcnt lgkmcnt(0)
	v_add_f32_e32 v0, v0, v1
	v_xor_b32_e32 v124, 0x80000000, v0
	v_lshrrev_b32_e32 v0, 3, v139
	v_lshlrev_b32_e32 v1, 4, v139
	v_mul_lo_u32 v0, v0, s0
	v_and_b32_e32 v1, 0x70, v1
	v_add3_u32 v129, v0, v1, 0
	v_lshlrev_b32_e32 v0, 1, v139
	v_and_b32_e32 v1, 3, v139
	v_and_or_b32 v0, v0, 24, v1
	v_max_u32_e32 v1, 8, v141
	v_sub_u32_e64 v2, v141, 8 clamp
	v_add_u32_e32 v1, 8, v1
	v_cmp_ge_u32_e32 vcc, v152, v2
	v_cmp_lt_u32_e64 s[4:5], v152, v1
	v_or_b32_e32 v3, 1, v152
	s_and_b64 s[4:5], vcc, s[4:5]
	v_cmp_ge_u32_e32 vcc, v3, v2
	v_cmp_lt_u32_e64 s[6:7], v3, v1
	v_or_b32_e32 v3, 2, v152
	s_and_b64 s[6:7], vcc, s[6:7]
	v_cmp_ge_u32_e32 vcc, v3, v2
	v_cmp_lt_u32_e64 s[8:9], v3, v1
	v_or_b32_e32 v3, 3, v152
	s_and_b64 s[8:9], vcc, s[8:9]
	v_cmp_ge_u32_e32 vcc, v3, v2
	v_cmp_lt_u32_e64 s[10:11], v3, v1
	v_or_b32_e32 v3, 4, v152
	s_and_b64 s[10:11], vcc, s[10:11]
	v_cmp_ge_u32_e32 vcc, v3, v2
	v_cmp_lt_u32_e64 s[12:13], v3, v1
	v_or_b32_e32 v3, 5, v152
	s_and_b64 s[12:13], vcc, s[12:13]
	v_cmp_ge_u32_e32 vcc, v3, v2
	v_cmp_lt_u32_e64 s[14:15], v3, v1
	v_or_b32_e32 v3, 6, v152
	s_and_b64 s[14:15], vcc, s[14:15]
	v_cmp_ge_u32_e32 vcc, v3, v2
	v_or_b32_e32 v2, 7, v152
	v_cmp_lt_u32_e64 s[16:17], v3, v1
	v_cmp_lt_u32_e64 s[18:19], v2, v1
	v_add_u32_e32 v2, 8, v152
	v_add_u32_e32 v3, 24, v141
	v_add_u32_e32 v1, 8, v141
	v_cmp_lt_u32_e64 s[20:21], v2, v3
	v_add_u32_e32 v2, 9, v152
	v_cmp_ge_u32_e64 s[22:23], v2, v1
	v_cmp_lt_u32_e64 s[24:25], v2, v3
	v_add_u32_e32 v2, 10, v152
	s_and_b64 s[22:23], s[22:23], s[24:25]
	v_cmp_ge_u32_e64 s[24:25], v2, v1
	v_cmp_lt_u32_e64 s[26:27], v2, v3
	v_add_u32_e32 v2, 11, v152
	s_and_b64 s[24:25], s[24:25], s[26:27]
	v_cmp_ge_u32_e64 s[26:27], v2, v1
	v_cmp_lt_u32_e64 s[28:29], v2, v3
	v_add_u32_e32 v2, 12, v152
	s_and_b64 s[26:27], s[26:27], s[28:29]
	v_cmp_ge_u32_e64 s[28:29], v2, v1
	v_cmp_lt_u32_e64 s[30:31], v2, v3
	v_add_u32_e32 v2, 13, v152
	s_and_b64 s[28:29], s[28:29], s[30:31]
	v_cmp_ge_u32_e64 s[30:31], v2, v1
	v_cmp_lt_u32_e64 s[34:35], v2, v3
	v_add_u32_e32 v2, 14, v152
	s_and_b64 s[30:31], s[30:31], s[34:35]
	v_cmp_ge_u32_e64 s[34:35], v2, v1
	v_cmp_lt_u32_e64 s[36:37], v2, v3
	v_add_u32_e32 v2, 15, v152
	s_and_b64 s[34:35], s[34:35], s[36:37]
	v_cmp_ge_u32_e64 s[36:37], v2, v1
	v_cmp_lt_u32_e64 s[38:39], v2, v3
	v_add_u32_e32 v1, 24, v152
	v_add_u32_e32 v2, 40, v141
	s_and_b64 s[16:17], vcc, s[16:17]
	v_cmp_ge_u32_e32 vcc, v152, v141
	s_and_b64 s[36:37], s[36:37], s[38:39]
	v_cmp_lt_u32_e64 s[38:39], v1, v2
	v_add_u32_e32 v1, 25, v152
	s_and_b64 s[20:21], vcc, s[20:21]
	s_and_b64 s[38:39], vcc, s[38:39]
	v_cmp_ge_u32_e32 vcc, v1, v3
; __device__ void na_super(char* lds, const Params& p, int layer, int su) {
;     ...
;     for (int st = 0; st < nsteps; ++st) {
;         const char* cur = lds + (st & 1) * NA_STAGE;
;         char* nxt = lds + ((st + 1) & 1) * NA_STAGE;
;         if (st + 1 < nsteps) {
;             const bf16_t* kg = Kg + (size_t)(st + 1) * 8192; const bf16_t* vg = Vg + (size_t)(st + 1) * 8192;
;             rk[0] = *(const u32x4*)(kg); rk[1] = *(const u32x4*)(kg + 4096);
;             rv[0] = *(const u32x4*)(vg); rv[1] = *(const u32x4*)(vg + 4096);
;         }
; #pragma unroll 1
;         for (int slot = 0; slot < 2; ++slot) {
;             const int kr = klo + 2 * st + slot;
;             if (kr >= rsw && kr <= rsw + 7) {
	v_cmp_lt_u32_e64 s[40:41], v1, v2
	v_add_u32_e32 v1, 26, v152
	s_and_b64 s[40:41], vcc, s[40:41]
	v_cmp_ge_u32_e32 vcc, v1, v3
	v_cmp_lt_u32_e64 s[42:43], v1, v2
	v_add_u32_e32 v1, 27, v152
	s_and_b64 s[42:43], vcc, s[42:43]
	v_cmp_ge_u32_e32 vcc, v1, v3
	v_cmp_lt_u32_e64 s[44:45], v1, v2
	v_add_u32_e32 v1, 28, v152
	s_and_b64 s[44:45], vcc, s[44:45]
	v_cmp_ge_u32_e32 vcc, v1, v3
	v_cmp_lt_u32_e64 s[46:47], v1, v2
	v_add_u32_e32 v1, 29, v152
	s_and_b64 s[46:47], vcc, s[46:47]
	v_cmp_ge_u32_e32 vcc, v1, v3
	v_cmp_lt_u32_e64 s[48:49], v1, v2
	v_add_u32_e32 v1, 30, v152
	s_and_b64 s[48:49], vcc, s[48:49]
	v_cmp_ge_u32_e32 vcc, v1, v3
	v_cmp_lt_u32_e64 s[50:51], v1, v2
	v_add_u32_e32 v1, 31, v152
	s_and_b64 s[50:51], vcc, s[50:51]
	v_cmp_ge_u32_e32 vcc, v1, v3
	v_cmp_lt_u32_e64 s[52:53], v1, v2
	v_min_u32_e32 v1, 8, v141
	v_add_u32_e32 v2, 40, v1
	v_or_b32_e32 v3, 32, v152
	v_add_u32_e32 v1, 56, v1
	s_and_b64 s[52:53], vcc, s[52:53]
	v_cmp_ge_u32_e32 vcc, v3, v2
	v_cmp_lt_u32_e64 s[54:55], v3, v1
	v_or_b32_e32 v3, 33, v152
	s_and_b64 s[54:55], vcc, s[54:55]
	v_cmp_ge_u32_e32 vcc, v3, v2
	v_cmp_lt_u32_e64 s[56:57], v3, v1
	v_or_b32_e32 v3, 34, v152
	s_and_b64 s[56:57], vcc, s[56:57]
	v_cmp_ge_u32_e32 vcc, v3, v2
	v_cmp_lt_u32_e64 s[58:59], v3, v1
	v_or_b32_e32 v3, 35, v152
	s_and_b64 s[58:59], vcc, s[58:59]
	v_cmp_ge_u32_e32 vcc, v3, v2
	v_cmp_lt_u32_e64 s[60:61], v3, v1
	v_or_b32_e32 v3, 36, v152
	s_and_b64 s[60:61], vcc, s[60:61]
	v_cmp_ge_u32_e32 vcc, v3, v2
	v_cmp_lt_u32_e64 s[62:63], v3, v1
	v_or_b32_e32 v3, 37, v152
	s_and_b64 s[62:63], vcc, s[62:63]
	v_cmp_ge_u32_e32 vcc, v3, v2
	v_cmp_lt_u32_e64 s[64:65], v3, v1
	v_or_b32_e32 v3, 38, v152
	v_mul_u32_u24_e32 v144, 0x90, v0
	v_sub_u32_e32 v0, v152, v141
	s_and_b64 s[64:65], vcc, s[64:65]
	v_cmp_ge_u32_e32 vcc, v3, v2
	v_cmp_lt_u32_e64 s[66:67], v3, v1
	v_or_b32_e32 v3, 39, v152
	s_and_b64 s[66:67], vcc, s[66:67]
	v_cmp_ge_u32_e32 vcc, v3, v2
	v_cmp_lt_u32_e64 s[68:69], v3, v1
	v_lshl_add_u32 v146, v0, 2, s70
	v_mov_b64_e32 v[32:33], v[48:49]
	v_mov_b64_e32 v[28:29], v[48:49]
	v_mov_b64_e32 v[24:25], v[48:49]
	v_mov_b64_e32 v[20:21], v[48:49]
	v_mov_b64_e32 v[16:17], v[48:49]
	v_mov_b64_e32 v[12:13], v[48:49]
	v_mov_b64_e32 v[8:9], v[48:49]
	v_mov_b64_e32 v[4:5], v[48:49]
	v_mov_b64_e32 v[0:1], v[48:49]
	s_add_i32 s97, s92, 7
	v_mov_b32_e32 v85, v84
	v_mov_b32_e32 v86, v84
	v_mov_b32_e32 v87, v84
	v_mov_b32_e32 v117, v116
	v_mov_b32_e32 v118, v116
	v_mov_b32_e32 v119, v116
	v_mov_b32_e32 v121, v120
	v_mov_b32_e32 v122, v120
	v_mov_b32_e32 v123, v120
	v_mov_b32_e32 v125, v124
	v_mov_b32_e32 v126, v124
	v_mov_b32_e32 v127, v124
	s_and_b64 s[68:69], vcc, s[68:69]
	v_mov_b64_e32 v[52:53], v[48:49]
	v_mov_b64_e32 v[72:73], v[48:49]
	v_mov_b64_e32 v[88:89], v[48:49]
	v_mov_b64_e32 v[46:47], v[50:51]
	v_mov_b64_e32 v[42:43], v[50:51]
	v_mov_b64_e32 v[38:39], v[50:51]
	v_mov_b64_e32 v[34:35], v[50:51]
	v_mov_b64_e32 v[30:31], v[50:51]
	v_mov_b64_e32 v[26:27], v[50:51]
	v_mov_b64_e32 v[22:23], v[50:51]
	v_mov_b64_e32 v[18:19], v[50:51]
	v_mov_b64_e32 v[14:15], v[50:51]
	v_mov_b64_e32 v[10:11], v[50:51]
	v_mov_b64_e32 v[6:7], v[50:51]
	v_mov_b64_e32 v[2:3], v[50:51]
	s_barrier
	s_waitcnt vmcnt(3)
	ds_write_b128 v129, v[100:103]
	s_waitcnt vmcnt(2)
	ds_write_b128 v129, v[104:107] offset:9216
	s_waitcnt vmcnt(1)
	ds_write_b128 v129, v[108:111] offset:18432
	s_waitcnt vmcnt(0)
	ds_write_b128 v129, v[112:115] offset:27648
	s_waitcnt lgkmcnt(0)
	s_barrier
.LBB0_454:
	s_add_i32 s70, s2, 1
	s_cmp_lt_u32 s70, s96
	s_cselect_b64 s[0:1], -1, 0
	s_cmp_ge_u32 s70, s96
	s_cbranch_scc1 .LBB0_456
	s_lshl_b64 s[76:77], s[70:71], 13
	s_add_i32 s100, s70, 8
	s_lshl_b32 s101, s96, 1
	s_cmp_lt_u32 s100, s101
	s_mov_b32 s100, 0x4000
	s_cselect_b32 s100, 0x10000, s100
	s_waitcnt vmcnt(2)
	v_lshl_add_u64 v[104:105], v[130:131], 0, s[76:77]
	global_load_dwordx4 v[100:103], v[104:105], off
	v_add_co_u32_e32 v104, vcc, s100, v104
	s_waitcnt vmcnt(1)
	v_lshl_add_u64 v[112:113], v[132:133], 0, s[76:77]
	v_addc_co_u32_e32 v105, vcc, 0, v105, vcc
	global_load_dwordx4 v[104:107], v[104:105], off
	s_nop 0
	global_load_dwordx4 v[108:111], v[112:113], off
	v_add_co_u32_e32 v112, vcc, s100, v112
	s_nop 1
	v_addc_co_u32_e32 v113, vcc, 0, v113, vcc
	global_load_dwordx4 v[112:115], v[112:113], off
.LBB0_456:
	s_bitcmp1_b32 s2, 0
	s_cselect_b32 s3, 0x9000, 0
	s_add_i32 s3, s3, 0
	s_add_i32 s101, s2, 8
	s_lshl_b32 s72, s96, 1
	s_cmp_lt_u32 s101, s72
	s_movk_i32 s101, 2
	s_cselect_b32 s101, 8, s101
	s_mov_b32 s72, s2
	s_mov_b32 s76, 0
	s_add_i32 s72, s72, s93
	v_add3_u32 v147, s3, v144, v128
	v_add3_u32 v148, s3, v145, v128
	s_mov_b64 s[2:3], -1
	s_branch .LBB0_458

; __device__ void na_super(char* lds, const Params& p, int layer, int su) {
;     ...
;         for (int slot = 0; slot < 2; ++slot) {
;             const int kr = klo + 2 * st + slot;
;             if (kr >= rsw && kr <= rsw + 7) {
;                 const char* cK = cur + slot * 64 * NA_P + krow_off;
;                 const char* cV = cur + NA_KBYTES + slot * 64 * NA_P + vrow_off;
;                 const float* rpr = rph + (kr - rq + 7) * 31;
;                 float v[4][8];
; #pragma unroll
;                 for (int n = 0; n < 4; ++n) {
;                     const int kcstart = n == 0 ? 0 : (n == 1 ? 8 : (n == 2 ? 24 : 32));
;                     const int qcol = 16 * n + fr;
;                     const float* bp = rpr + (kcstart + 8 * fq - qcol + 15);
; #pragma unroll
;                     for (int e = 0; e < 8; ++e) v[n][e] = bp[e];
;                 }
; #pragma unroll
;                 for (int np = 0; np < 2; ++np) {
;                     bf16x8 kfr[2][4];
; #pragma unroll
;                     for (int q = 0; q < 2; ++q) {
;                         const int n = 2 * np + q;
;                         const int kcstart = n == 0 ? 0 : (n == 1 ? 8 : (n == 2 ? 24 : 32));
; #pragma unroll
;                         for (int T = 0; T < 2; ++T) { kfr[q][2 * T] = *(const bf16x8*)(cK + (kcstart + T * 4) * NA_P); kfr[q][2 * T + 1] = *(const bf16x8*)(cK + (kcstart + T * 4) * NA_P + 64); }
;                     }
; #pragma unroll
;                     for (int q = 0; q < 2; ++q) {
;                         const int n = 2 * np + q;
;                         const int kcstart = n == 0 ? 0 : (n == 1 ? 8 : (n == 2 ? 24 : 32));
;                         const int qcol = 16 * n + fr;
;                         const int qcstart = min(max(qcol - 8, 0), 48);
; #pragma unroll
;                         for (int T = 0; T < 2; ++T) {
;                             f32x4 s = (f32x4){mrow[n], mrow[n], mrow[n], mrow[n]};
;                             s = __builtin_amdgcn_mfma_f32_16x16x32_bf16(kfr[q][2 * T], qf[n][0], s, 0, 0, 0);
;                             s = __builtin_amdgcn_mfma_f32_16x16x32_bf16(kfr[q][2 * T + 1], qf[n][1], s, 0, 0, 0);
; #pragma unroll
;                             for (int e = 0; e < 4; ++e) {
;                                 const int kcol = kcstart + 8 * fq + e + 4 * T;
.LBB0_458:
	s_mul_i32 s77, s76, s101
	s_add_i32 s77, s77, s72
	s_cmp_lt_u32 s77, s92
	s_cselect_b64 s[78:79], -1, 0
	s_cmp_gt_u32 s77, s97
	s_cselect_b64 s[80:81], -1, 0
	s_or_b64 s[78:79], s[78:79], s[80:81]
	s_and_b64 vcc, exec, s[78:79]
	s_cbranch_vccnz .LBB0_457
	s_sub_i32 s77, s77, s74
	s_mulk_i32 s77, 0x7c
	s_mulk_i32 s76, 0x2400
	v_add_u32_e32 v154, s77, v146
	v_add_u32_e32 v149, s76, v147
	ds_read2_b32 v[150:151], v154 offset0:232 offset1:233
	ds_read2_b32 v[156:157], v154 offset0:234 offset1:235
	ds_read2_b32 v[158:159], v154 offset0:236 offset1:237
	ds_read2_b32 v[160:161], v154 offset0:238 offset1:239
	ds_read_b128 v[164:167], v149
	ds_read2_b32 v[162:163], v154 offset0:224 offset1:225
	ds_read2_b32 v[196:197], v154 offset0:226 offset1:227
	ds_read2_b32 v[198:199], v154 offset0:228 offset1:229
	ds_read2_b32 v[200:201], v154 offset0:230 offset1:231
	ds_read_b128 v[168:171], v149 offset:64
	ds_read2_b32 v[202:203], v154 offset0:216 offset1:217
	ds_read2_b32 v[204:205], v154 offset0:218 offset1:219
	ds_read2_b32 v[206:207], v154 offset0:220 offset1:221
	ds_read2_b32 v[208:209], v154 offset0:222 offset1:223
	ds_read_b128 v[172:175], v149 offset:576
	ds_read_b128 v[176:179], v149 offset:640
	s_waitcnt lgkmcnt(11)
	v_mfma_f32_16x16x32_bf16 v[164:167], v[164:167], v[56:59], v[84:87]
	ds_read_b128 v[180:183], v149 offset:1152
	ds_read_b128 v[184:187], v149 offset:1216
	ds_read_b128 v[188:191], v149 offset:1728
	ds_read_b128 v[192:195], v149 offset:1792
	v_add_u32_e32 v226, s76, v148
	s_waitcnt lgkmcnt(10)
	v_mfma_f32_16x16x32_bf16 v[164:167], v[168:171], v[60:63], v[164:167]
	s_waitcnt lgkmcnt(5)
	v_mfma_f32_16x16x32_bf16 v[168:171], v[172:175], v[56:59], v[84:87]
	s_nop 5
	v_fmac_f32_e32 v151, 0x3e38aa3b, v165
	v_fmamk_f32 v150, v164, 0x3e38aa3b, v150
	v_cndmask_b32_e64 v154, v243, v151, s[6:7]
	v_fmamk_f32 v151, v166, 0x3e38aa3b, v156
	v_fmac_f32_e32 v157, 0x3e38aa3b, v167
	s_waitcnt lgkmcnt(4)
	v_mfma_f32_16x16x32_bf16 v[164:167], v[176:179], v[60:63], v[168:171]
	v_cndmask_b32_e64 v156, v243, v151, s[8:9]
	v_cndmask_b32_e64 v150, v243, v150, s[4:5]
	v_cndmask_b32_e64 v210, v243, v157, s[10:11]
	s_waitcnt lgkmcnt(3)
	v_mfma_f32_16x16x32_bf16 v[168:171], v[180:183], v[64:67], v[116:119]
	v_exp_f32_e32 v157, v154
	s_nop 1
	v_fmamk_f32 v151, v164, 0x3e38aa3b, v158
	v_cndmask_b32_e64 v158, v243, v151, s[12:13]
	v_fmac_f32_e32 v159, 0x3e38aa3b, v165
	v_fmamk_f32 v151, v166, 0x3e38aa3b, v160
	v_fmac_f32_e32 v161, 0x3e38aa3b, v167
	s_waitcnt lgkmcnt(2)
	v_mfma_f32_16x16x32_bf16 v[164:167], v[184:187], v[68:71], v[168:171]
	v_cndmask_b32_e64 v160, v243, v151, s[16:17]
	v_cndmask_b32_e64 v211, v243, v159, s[14:15]
	v_cndmask_b32_e64 v212, v243, v161, s[18:19]
	s_waitcnt lgkmcnt(1)
	v_mfma_f32_16x16x32_bf16 v[168:171], v[188:191], v[64:67], v[116:119]
	v_exp_f32_e32 v159, v156
	s_nop 1
	v_fmamk_f32 v151, v164, 0x3e38aa3b, v162
	v_cndmask_b32_e64 v213, v243, v151, s[20:21]
	v_fmamk_f32 v151, v165, 0x3e38aa3b, v163
	v_cndmask_b32_e64 v214, v243, v151, s[22:23]
	v_fmamk_f32 v151, v166, 0x3e38aa3b, v196
	v_cndmask_b32_e64 v215, v243, v151, s[24:25]
	v_fmamk_f32 v151, v167, 0x3e38aa3b, v197
	s_waitcnt lgkmcnt(0)
	v_mfma_f32_16x16x32_bf16 v[164:167], v[192:195], v[68:71], v[168:171]
	v_cndmask_b32_e64 v216, v243, v151, s[26:27]
	v_exp_f32_e32 v161, v210
	v_exp_f32_e32 v156, v214
	ds_read_b128 v[168:171], v149 offset:3456
	s_nop 3
	v_fmamk_f32 v151, v164, 0x3e38aa3b, v198
	v_cndmask_b32_e64 v217, v243, v151, s[28:29]
	v_fmamk_f32 v151, v165, 0x3e38aa3b, v199
	v_cndmask_b32_e64 v218, v243, v151, s[30:31]
	v_fmamk_f32 v151, v166, 0x3e38aa3b, v200
	v_cndmask_b32_e64 v219, v243, v151, s[34:35]
	v_fmamk_f32 v151, v167, 0x3e38aa3b, v201
	ds_read_b128 v[164:167], v149 offset:3520
	ds_read_b128 v[172:175], v149 offset:4032
	ds_read_b128 v[176:179], v149 offset:4096
	s_waitcnt lgkmcnt(3)
	v_mfma_f32_16x16x32_bf16 v[168:171], v[168:171], v[76:79], v[120:123]
	ds_read_b128 v[180:183], v149 offset:4608
	ds_read_b128 v[184:187], v149 offset:4672
	ds_read_b128 v[188:191], v149 offset:5184
	ds_read_b128 v[192:195], v149 offset:5248
	v_cndmask_b32_e64 v220, v243, v151, s[36:37]
	s_waitcnt lgkmcnt(6)
	v_mfma_f32_16x16x32_bf16 v[164:167], v[164:167], v[80:83], v[168:171]
	s_waitcnt lgkmcnt(5)
	v_mfma_f32_16x16x32_bf16 v[168:171], v[172:175], v[76:79], v[120:123]
	s_nop 5
	v_fmamk_f32 v149, v164, 0x3e38aa3b, v162
	v_fmac_f32_e32 v163, 0x3e38aa3b, v165
	v_fmamk_f32 v151, v166, 0x3e38aa3b, v196
	v_fmac_f32_e32 v197, 0x3e38aa3b, v167
	s_waitcnt lgkmcnt(4)
	v_mfma_f32_16x16x32_bf16 v[164:167], v[176:179], v[80:83], v[168:171]
	v_cndmask_b32_e64 v222, v243, v151, s[42:43]
	ds_read_b128 v[176:179], v226 offset:20736
	v_cndmask_b32_e64 v221, v243, v163, s[40:41]
	s_waitcnt lgkmcnt(4)
	v_mfma_f32_16x16x32_bf16 v[168:171], v[180:183], v[92:95], v[124:127]
	v_cndmask_b32_e64 v223, v243, v197, s[44:45]
	s_nop 1
	v_fmamk_f32 v151, v164, 0x3e38aa3b, v198
	v_cndmask_b32_e64 v198, v243, v151, s[46:47]
	v_fmac_f32_e32 v199, 0x3e38aa3b, v165
	v_fmamk_f32 v151, v166, 0x3e38aa3b, v200
	v_fmac_f32_e32 v201, 0x3e38aa3b, v167
	s_waitcnt lgkmcnt(3)
	v_mfma_f32_16x16x32_bf16 v[164:167], v[184:187], v[96:99], v[168:171]
	v_cndmask_b32_e64 v200, v243, v151, s[50:51]
	v_exp_f32_e32 v163, v158
	v_exp_f32_e32 v197, v212
	s_waitcnt lgkmcnt(2)
; __device__ __forceinline__ float fast_exp2(float x) { return __builtin_amdgcn_exp2f(x); }
; __device__ void na_super(char* lds, const Params& p, int layer, int su) {
;     ...
; #pragma unroll
;                 for (int n = 0; n < 4; ++n) {
;                     const int kcstart = n == 0 ? 0 : (n == 1 ? 8 : (n == 2 ? 24 : 32));
;                     float ps = 0.f;
; #pragma unroll
;                     for (int e = 0; e < 8; ++e) { v[n][e] = fast_exp2(v[n][e]); ps += v[n][e]; }
;                     lrow[n] += ps;
;                     u32x4 w;
;                     w.x = cvt_pk_bf16(v[n][0], v[n][1]); w.y = cvt_pk_bf16(v[n][2], v[n][3]); w.z = cvt_pk_bf16(v[n][4], v[n][5]); w.w = cvt_pk_bf16(v[n][6], v[n][7]);
;                     const bf16x8 pb = __builtin_bit_cast(bf16x8, w);
; #pragma unroll
;                     for (int dt = 0; dt < 4; ++dt) {
;                         const bf16x8 vf = *(const bf16x8*)(cV + dt * 16 * NA_P + kcstart * 2);
;                         O[n][dt] = __builtin_amdgcn_mfma_f32_16x16x32_bf16(vf, pb, O[n][dt], 0, 0, 0);
;                     }
;                 }
	v_mfma_f32_16x16x32_bf16 v[168:171], v[188:191], v[92:95], v[124:127]
	v_cvt_pk_bf16_f32 v173, v159, v161
	s_nop 1
	v_fmamk_f32 v151, v164, 0x3e38aa3b, v202
	v_cndmask_b32_e64 v202, v243, v151, s[54:55]
	v_fmac_f32_e32 v203, 0x3e38aa3b, v165
	v_fmamk_f32 v151, v166, 0x3e38aa3b, v204
	v_fmac_f32_e32 v205, 0x3e38aa3b, v167
	s_waitcnt lgkmcnt(1)
	v_mfma_f32_16x16x32_bf16 v[164:167], v[192:195], v[96:99], v[168:171]
	v_cndmask_b32_e64 v204, v243, v151, s[58:59]
	v_exp_f32_e32 v151, v150
	v_exp_f32_e32 v193, v211
	ds_read_b128 v[168:171], v226 offset:18432
	v_exp_f32_e32 v195, v160
	ds_read_b128 v[180:183], v226 offset:18448
	ds_read_b128 v[184:187], v226 offset:23040
	v_cvt_pk_bf16_f32 v172, v151, v157
	v_cvt_pk_bf16_f32 v174, v163, v193
	v_cvt_pk_bf16_f32 v175, v195, v197
	v_fmamk_f32 v150, v164, 0x3e38aa3b, v206
	v_cndmask_b32_e64 v154, v243, v205, s[60:61]
	s_waitcnt lgkmcnt(2)
	v_mfma_f32_16x16x32_bf16 v[88:91], v[168:171], v[172:175], v[88:91]
	ds_read_b128 v[168:171], v226 offset:25344
	ds_read_b128 v[188:191], v226 offset:20752
	v_cndmask_b32_e64 v205, v243, v150, s[62:63]
	v_exp_f32_e32 v150, v213
	v_mfma_f32_16x16x32_bf16 v[72:75], v[176:179], v[172:175], v[72:75]
	ds_read_b128 v[176:179], v226 offset:23056
	v_fmac_f32_e32 v207, 0x3e38aa3b, v165
	v_exp_f32_e32 v158, v215
	s_waitcnt lgkmcnt(3)
	v_mfma_f32_16x16x32_bf16 v[52:55], v[184:187], v[172:175], v[52:55]
	ds_read_b128 v[184:187], v226 offset:25360
	v_exp_f32_e32 v160, v216
	v_exp_f32_e32 v162, v217
	v_exp_f32_e32 v192, v218
	v_exp_f32_e32 v194, v219
	v_exp_f32_e32 v196, v220
	v_fmamk_f32 v164, v166, 0x3e38aa3b, v208
	v_cndmask_b32_e64 v206, v243, v207, s[64:65]
	s_waitcnt lgkmcnt(3)
	v_mfma_f32_16x16x32_bf16 v[48:51], v[168:171], v[172:175], v[48:51]
	v_cndmask_b32_e64 v207, v243, v164, s[66:67]
	v_fmac_f32_e32 v209, 0x3e38aa3b, v167
	ds_read_b128 v[164:167], v226 offset:18480
	ds_read_b128 v[172:175], v226 offset:20784
	v_cvt_pk_bf16_f32 v168, v150, v156
	v_pk_add_f32 v[150:151], v[150:151], 0 op_sel_hi:[1,0]
	v_cndmask_b32_e64 v149, v243, v149, s[38:39]
	v_pk_add_f32 v[150:151], v[156:157], v[150:151]
	v_cndmask_b32_e64 v199, v243, v199, s[48:49]
	v_cndmask_b32_e64 v224, v243, v201, s[52:53]
	v_cvt_pk_bf16_f32 v169, v158, v160
	v_cvt_pk_bf16_f32 v170, v162, v192
	v_cvt_pk_bf16_f32 v171, v194, v196
	v_pk_add_f32 v[150:151], v[158:159], v[150:151]
	v_cndmask_b32_e64 v225, v243, v203, s[56:57]
	s_waitcnt lgkmcnt(4)
	v_mfma_f32_16x16x32_bf16 v[40:43], v[188:191], v[168:171], v[40:43]
	v_add_f32_e64 v150, v160, v150
	v_add_f32_e64 v151, v161, v151
	v_exp_f32_e32 v157, v149
	v_exp_f32_e32 v159, v221
	v_exp_f32_e32 v161, v222
	v_exp_f32_e32 v189, v223
	v_exp_f32_e32 v191, v198
	v_exp_f32_e32 v199, v199
	v_exp_f32_e32 v201, v200
	v_exp_f32_e32 v203, v224
	v_mfma_f32_16x16x32_bf16 v[44:47], v[180:183], v[168:171], v[44:47]
	v_add_f32_e64 v150, v162, v150
	v_add_f32_e64 v151, v163, v151
	v_exp_f32_e32 v156, v202
	v_pk_add_f32 v[150:151], v[192:193], v[150:151]
	s_waitcnt lgkmcnt(3)
	v_mfma_f32_16x16x32_bf16 v[36:39], v[176:179], v[168:171], v[36:39]
	ds_read_b128 v[176:179], v226 offset:23088
	ds_read_b128 v[180:183], v226 offset:18496
	v_exp_f32_e32 v158, v225
	v_pk_add_f32 v[150:151], v[194:195], v[150:151]
	s_waitcnt lgkmcnt(4)
	v_mfma_f32_16x16x32_bf16 v[32:35], v[184:187], v[168:171], v[32:35]
	v_cvt_pk_bf16_f32 v168, v157, v159
	v_cvt_pk_bf16_f32 v169, v161, v189
	v_cvt_pk_bf16_f32 v170, v191, v199
	v_cvt_pk_bf16_f32 v171, v201, v203
	v_exp_f32_e32 v160, v204
	v_cndmask_b32_e64 v208, v243, v209, s[68:69]
	s_waitcnt lgkmcnt(3)
	v_mfma_f32_16x16x32_bf16 v[28:31], v[164:167], v[168:171], v[28:31]
	ds_read_b128 v[164:167], v226 offset:25392
	ds_read_b128 v[184:187], v226 offset:20800
	v_pk_add_f32 v[150:151], v[196:197], v[150:151]
	v_exp_f32_e32 v188, v154
	s_waitcnt lgkmcnt(4)
	v_mfma_f32_16x16x32_bf16 v[24:27], v[172:175], v[168:171], v[24:27]
	ds_read_b128 v[172:175], v226 offset:23104
	v_pk_add_f32 v[136:137], v[136:137], v[150:151]
	v_exp_f32_e32 v190, v205
	s_waitcnt lgkmcnt(4)
	v_mfma_f32_16x16x32_bf16 v[20:23], v[176:179], v[168:171], v[20:23]
	ds_read_b128 v[176:179], v226 offset:25408
	v_exp_f32_e32 v198, v206
	v_exp_f32_e32 v200, v207
	v_exp_f32_e32 v202, v208
	v_pk_add_f32 v[150:151], v[156:157], 0 op_sel_hi:[1,0]
	s_waitcnt lgkmcnt(3)
	v_mfma_f32_16x16x32_bf16 v[16:19], v[164:167], v[168:171], v[16:19]
	v_add_f32_e64 v150, v158, v150
	v_add_f32_e64 v151, v159, v151
	v_cvt_pk_bf16_f32 v164, v156, v158
	v_pk_add_f32 v[150:151], v[160:161], v[150:151]
	v_cvt_pk_bf16_f32 v165, v160, v188
	v_pk_add_f32 v[150:151], v[188:189], v[150:151]
	v_cvt_pk_bf16_f32 v166, v190, v198
	v_cvt_pk_bf16_f32 v167, v200, v202
	v_pk_add_f32 v[150:151], v[190:191], v[150:151]
	s_nop 0
	v_mfma_f32_16x16x32_bf16 v[12:15], v[180:183], v[164:167], v[12:15]
	v_add_f32_e64 v150, v198, v150
	v_add_f32_e64 v151, v199, v151
	v_pk_add_f32 v[150:151], v[200:201], v[150:151]
	s_waitcnt lgkmcnt(2)
	v_mfma_f32_16x16x32_bf16 v[8:11], v[184:187], v[164:167], v[8:11]
	v_add_f32_e64 v150, v202, v150
	v_add_f32_e64 v151, v203, v151
	v_pk_add_f32 v[134:135], v[134:135], v[150:151]
	s_waitcnt lgkmcnt(1)
	v_mfma_f32_16x16x32_bf16 v[4:7], v[172:175], v[164:167], v[4:7]
	s_waitcnt lgkmcnt(0)
	v_mfma_f32_16x16x32_bf16 v[0:3], v[176:179], v[164:167], v[0:3]
	s_branch .LBB0_457

; __device__ __forceinline__ float bflo(unsigned w) { return __uint_as_float(w << 16); }
; __device__ void da_unit(char* lds, const Params& p, int layer, int unit) {
;     int tid_ = threadIdx.x; asm volatile("" : "+v"(tid_)); const int tid = tid_, lane = tid & 63, wid = __builtin_amdgcn_readfirstlane(tid >> 6), r = lane & 31, h2 = lane >> 5;
;     const int c = wid & 1, qg = wid >> 1;
;     const int g8 = unit >> 3, bh = (unit & 7) * 4 + (g8 >> 4), qb = g8 & 15, b = bh >> 2, h = bh & 3;
;     const float slope2 = exp2f(-2.0f * (float)(h + 1)) * LOG2E;
;     const float qscale = 0.125f * LOG2E;
;     float lam;
;     {
;         const float v1 = p.lq1[layer * 64 + lane] * p.lk1[layer * 64 + lane], v2 = p.lq2[layer * 64 + lane] * p.lk2[layer * 64 + lane];
;         float s1 = v1, s2 = v2;
; #pragma unroll
;         for (int s = 32; s >= 1; s >>= 1) { s1 += __shfl_xor(s1, s); s2 += __shfl_xor(s2, s); }
;         lam = __expf(s1) - __expf(s2) + p.lam_init[layer];
;     }
;     const int q0 = qb * 128 + qg * 32;
;     const size_t tokq = (size_t)b * SEQ + q0 + r;
;     bf16x8 qf[4];
; #pragma unroll
;     for (int t = 0; t < 4; ++t) {
;         const u32x4 w = *(const u32x4*)(p.z + ZS_QD + ((size_t)(bh * 2048 + q0 + r)) * 128 + c * 64 + t * 16 + h2 * 8);
;         u32x4 o;
;         o.x = cvt_pk_bf16(bflo(w.x) * qscale, bfhi(w.x) * qscale); o.y = cvt_pk_bf16(bflo(w.y) * qscale, bfhi(w.y) * qscale);
;         o.z = cvt_pk_bf16(bflo(w.z) * qscale, bfhi(w.z) * qscale); o.w = cvt_pk_bf16(bflo(w.w) * qscale, bfhi(w.w) * qscale);
;         qf[t] = __builtin_bit_cast(bf16x8, o);
;     }
;     f32x16 O[4], Bs;
; #pragma unroll
;     for (int k = 0; k < 4; ++k)
; #pragma unroll
;         for (int e = 0; e < 16; ++e) O[k][e] = 0.f;
; #pragma unroll
;     for (int e = 0; e < 16; ++e) Bs[e] = -slope2 * (float)(16 * (e >> 3) + (e & 7));
;     float mrow = -1e30f, lrow = 0.f;
;     const float qrel = (float)(8 * h2) - (float)(q0 + r);
;     const bf16_t* Kg = p.z + ZS_KD + ((size_t)bh * 2048) * 128 + tid * 8;
;     const bf16_t* Vg = p.vT + VS_VD + ((size_t)bh * 32) * 8192 + tid * 8;
;     const int kr_ = tid >> 4, kc_ = tid & 15, vr_ = tid >> 3, vc_ = tid & 7;
;     constexpr int NT = SEQ / 128;
;     auto tile_of = [&](int i) { return (i < NT - qb) ? (qb + i) : (NT - 1 - i); };
;     u32x4 rk[4], rv[4];
;     {
;         const int t0 = tile_of(0);
; #pragma unroll
.LBB0_475:
	s_and_b64 vcc, exec, s[0:1]
	s_cbranch_vccz .LBB0_451
	v_mov_b32_e32 v187, v245
	v_readlane_b32 s0, v255, 36
	v_and_b32_e32 v184, 63, v187
	s_bfe_u32 s14, s21, 0x40003
	v_or_b32_e32 v152, s0, v184
	v_readlane_b32 s0, v254, 60
	v_lshlrev_b64 v[0:1], 2, v[152:153]
	v_readlane_b32 s1, v254, 61
	v_readlane_b32 s2, v254, 62
	v_readlane_b32 s3, v254, 63
	v_lshl_add_u64 v[2:3], s[0:1], 0, v[0:1]
	global_load_dword v8, v[2:3], off
	v_lshl_add_u64 v[2:3], s[2:3], 0, v[0:1]
	global_load_dword v9, v[2:3], off
	v_readlane_b32 s4, v255, 0
	v_readlane_b32 s5, v255, 1
	v_readlane_b32 s6, v255, 2
	v_readlane_b32 s7, v255, 3
	v_lshl_add_u64 v[2:3], s[4:5], 0, v[0:1]
	global_load_dword v50, v[2:3], off
	v_lshl_add_u64 v[0:1], s[6:7], 0, v[0:1]
	global_load_dword v51, v[0:1], off
	s_lshl_b32 s0, s21, 2
	s_ashr_i32 s1, s21, 7
	s_and_b32 s2, s0, 28
	v_readfirstlane_b32 s3, v187
	s_and_b32 s12, s1, 3
	s_add_i32 s6, s2, s1
	s_bfe_u32 s13, s3, 0x20006
	s_lshl_b32 s0, s14, 7
	s_not_b32 s4, s12
	s_ashr_i32 s7, s6, 31
	s_lshl_b32 s5, s13, 5
	v_and_b32_e32 v0, 64, v240
	s_ashr_i32 s10, s3, 6
	s_lshl_b32 s1, s4, 1
	s_lshl_b32 s4, s6, 11
	s_lshl_b64 s[2:3], s[6:7], 19
	s_add_i32 s7, s5, s0
	v_xor_b32_e32 v1, 32, v240
	v_add_u32_e32 v52, 64, v0
	s_waitcnt vmcnt(0)
	v_and_b32_e32 v147, 31, v187
	s_lshr_b32 s15, s10, 2
	s_add_i32 s4, s7, s4
	v_cmp_lt_i32_e32 vcc, v1, v52
	s_lshl_b32 s8, s15, 7
	v_or_b32_e32 v2, s4, v147
	v_readlane_b32 s4, v254, 18
	v_cndmask_b32_e32 v1, v240, v1, vcc
	v_lshlrev_b32_e32 v0, 3, v187
	s_add_u32 s4, s4, s2
	v_readlane_b32 s5, v254, 19
	v_lshlrev_b32_e32 v244, 2, v1
	v_ashrrev_i32_e32 v1, 31, v0
	s_addc_u32 s5, s5, s3
	v_lshlrev_b64 v[0:1], 1, v[0:1]
	s_add_u32 s2, s60, s2
	v_lshl_add_u64 v[148:149], s[4:5], 0, v[0:1]
	s_addc_u32 s3, s61, s3
	s_lshl_b32 s70, s14, 15
	v_lshl_add_u64 v[164:165], v[148:149], 0, s[70:71]
	v_lshl_add_u64 v[150:151], s[2:3], 0, v[0:1]
	v_add_co_u32_e32 v0, vcc, s47, v164
	s_movk_i32 s2, 0x4000
	s_nop 0
	v_addc_co_u32_e32 v1, vcc, 0, v165, vcc
	v_add_co_u32_e32 v4, vcc, s2, v164
	s_movk_i32 s3, 0x6000
	s_nop 0
	v_addc_co_u32_e32 v5, vcc, 0, v165, vcc
	v_add_co_u32_e32 v6, vcc, s3, v164
	v_lshl_add_u64 v[166:167], v[150:151], 0, s[70:71]
	s_nop 0
	v_addc_co_u32_e32 v7, vcc, 0, v165, vcc
	global_load_dwordx4 v[18:21], v[164:165], off
	global_load_dwordx4 v[22:25], v[166:167], off
	global_load_dwordx4 v[26:29], v[0:1], off
	v_add_co_u32_e32 v0, vcc, s47, v166
	global_load_dwordx4 v[30:33], v[4:5], off
	global_load_dwordx4 v[34:37], v[6:7], off
	v_ashrrev_i32_e32 v3, 31, v2
	v_addc_co_u32_e32 v1, vcc, 0, v167, vcc
	v_lshlrev_b64 v[2:3], 8, v[2:3]
	v_add_co_u32_e32 v4, vcc, s2, v166
	s_mov_b32 s9, s71
	v_bfe_u32 v188, v187, 5, 1
	v_lshl_add_u64 v[2:3], s[58:59], 0, v[2:3]
	v_addc_co_u32_e32 v5, vcc, 0, v167, vcc
	s_waitcnt vmcnt(0)
	v_mul_f32_e32 v6, v8, v9
	ds_bpermute_b32 v53, v244, v6
	global_load_dwordx4 v[38:41], v[0:1], off
	global_load_dwordx4 v[42:45], v[4:5], off
	v_lshlrev_b32_e32 v152, 4, v188
	v_lshl_add_u64 v[2:3], v[2:3], 0, s[8:9]
	v_lshl_add_u64 v[12:13], v[2:3], 0, v[152:153]
	s_waitcnt lgkmcnt(0)
	v_fmac_f32_e32 v53, v8, v9
	v_mul_f32_e32 v0, v50, v51
	ds_bpermute_b32 v54, v244, v0
	v_add_co_u32_e32 v0, vcc, s3, v166
	s_movk_i32 s3, 0x110
	s_nop 0
	v_addc_co_u32_e32 v1, vcc, 0, v167, vcc
	global_load_dwordx4 v[46:49], v[0:1], off
	global_load_dwordx4 v[8:11], v[12:13], off
	global_load_dwordx4 v[4:7], v[12:13], off offset:32
	s_nop 0
	global_load_dwordx4 v[0:3], v[12:13], off offset:64
	global_load_dwordx4 v[14:17], v[12:13], off offset:96
	v_xor_b32_e32 v12, 16, v240
	v_cmp_lt_i32_e32 vcc, v12, v52
	s_waitcnt lgkmcnt(0)
	v_fmac_f32_e32 v54, v50, v51
	v_xor_b32_e32 v50, 8, v240
	v_cndmask_b32_e32 v12, v240, v12, vcc
	v_lshlrev_b32_e32 v12, 2, v12
	ds_bpermute_b32 v13, v12, v53
	ds_bpermute_b32 v12, v12, v54
	v_cmp_lt_i32_e32 vcc, v50, v52
	s_lshl_b32 s2, s14, 14
	s_cmp_lt_i32 s10, 4
	v_cndmask_b32_e32 v50, v240, v50, vcc
	s_waitcnt lgkmcnt(1)
	v_add_f32_e32 v13, v53, v13
	s_waitcnt lgkmcnt(0)
	v_add_f32_e32 v12, v54, v12
	v_lshlrev_b32_e32 v50, 2, v50
	ds_bpermute_b32 v51, v50, v13
	ds_bpermute_b32 v50, v50, v12
	s_waitcnt lgkmcnt(0)
	s_barrier
	v_add_f32_e32 v13, v13, v51
	v_add_f32_e32 v12, v12, v50
	v_xor_b32_e32 v50, 4, v240
	v_cmp_lt_i32_e32 vcc, v50, v52
	s_nop 1
	v_cndmask_b32_e32 v50, v240, v50, vcc
	v_lshlrev_b32_e32 v50, 2, v50
	ds_bpermute_b32 v51, v50, v13
	ds_bpermute_b32 v50, v50, v12
	s_waitcnt lgkmcnt(1)
	v_add_f32_e32 v13, v13, v51
	s_waitcnt lgkmcnt(0)
	v_add_f32_e32 v12, v12, v50
	v_xor_b32_e32 v50, 2, v240
	v_cmp_lt_i32_e32 vcc, v50, v52
	s_nop 1
	v_cndmask_b32_e32 v50, v240, v50, vcc
	v_lshlrev_b32_e32 v50, 2, v50
	ds_bpermute_b32 v51, v50, v13
	ds_bpermute_b32 v50, v50, v12
	s_waitcnt lgkmcnt(1)
	v_add_f32_e32 v170, v13, v51
	s_waitcnt lgkmcnt(0)
	v_add_f32_e32 v171, v12, v50
	v_xor_b32_e32 v12, 1, v240
	v_cmp_lt_i32_e32 vcc, v12, v52
	v_lshrrev_b32_e32 v13, 3, v187
	v_lshlrev_b32_e32 v50, 4, v187
	v_cndmask_b32_e32 v12, v240, v12, vcc
	v_lshlrev_b32_e32 v12, 2, v12
	ds_bpermute_b32 v172, v12, v170
	ds_bpermute_b32 v173, v12, v171
	v_lshrrev_b32_e32 v12, 4, v187
	v_mul_lo_u32 v182, v12, s3
	s_movk_i32 s3, 0x90
	v_and_b32_e32 v180, 0xf0, v50
	v_mul_lo_u32 v183, v13, s3
	v_add_u32_e32 v51, 0, v180
	v_and_b32_e32 v181, 0x70, v50
	v_add_u32_e32 v12, 0, v183
	v_add_u32_e32 v189, v51, v182
	v_add_u32_e32 v190, v12, v181
	ds_write_b128 v189, v[18:21]
	ds_write_b128 v190, v[22:25] offset:34816
	ds_write_b128 v189, v[26:29] offset:8704
	s_waitcnt vmcnt(6)
	ds_write_b128 v190, v[38:41] offset:44032
	ds_write_b128 v189, v[30:33] offset:17408
	s_waitcnt vmcnt(5)
	ds_write_b128 v190, v[42:45] offset:53248
	ds_write_b128 v189, v[34:37] offset:26112
	s_waitcnt vmcnt(4)
	ds_write_b128 v190, v[46:49] offset:62464
	s_waitcnt lgkmcnt(0)
	s_barrier
	s_cbranch_scc1 .LBB0_478
	s_setprio 1
